# NSA selected branch fast path: priority level 3 (was 1) across the compute segment
# baseline (speedup 1.0000x reference)
; DI void nsa_item(const Params& p, int bk, int qb, char* smem, float Mb) {
;     ...
;                 for (int k4 = 0; k4 < 4; ++k4) {
;                     kf[k4][0] = *(const bf16x8*)(kb_ + k4 * 16 * 144); kf[k4][1] = *(const bf16x8*)(kb_ + k4 * 16 * 144 + 64);
;                     vf[k4][0] = *(const bf16x8*)(kb_ + 9216 + k4 * 16 * 144); vf[k4][1] = *(const bf16x8*)(kb_ + 9216 + k4 * 16 * 144 + 64);
;                 }
;                 const bool mine = (sub >> fr) & 1u;
;                 const float Ml = mine ? Mb : 3.0e38f;
;                 const bool diag = (j == cur);
; #pragma unroll
;                 for (int g = 0; g < 3; ++g) {
;                     f32x4 st[4];
;                     st_from(kf, qf[g], st, -Ml);
;                     if (diag) {
; #pragma unroll
;                         for (int k4 = 0; k4 < 4; ++k4)
; #pragma unroll
;                             for (int ii = 0; ii < 4; ++ii) {
;                                 const float pv = (j * 64 + k4 * 16 + fq * 4 + ii <= tq) ? __builtin_amdgcn_exp2f(st[k4][ii]) : 0.f;
;                                 st[k4][ii] = pv; ls[g] += pv;
;                             }
;                     } else {
; #pragma unroll
;                         for (int k4 = 0; k4 < 4; ++k4)
; #pragma unroll
;                             for (int ii = 0; ii < 4; ++ii) { const float pv = __builtin_amdgcn_exp2f(st[k4][ii]); st[k4][ii] = pv; ls[g] += pv; }
;                     }
;                     pv_from(vf, st, o[g]);
.Lsel_fast:
	s_setprio 3
	ds_read_b128 v[140:143], v116 offset:6976
	ds_read_b128 v[108:111], v116 offset:9216
	ds_read_b128 v[88:91], v116 offset:9280
	ds_read_b128 v[92:95], v116 offset:11520
	ds_read_b128 v[96:99], v116 offset:11584
	ds_read_b128 v[100:103], v116 offset:13824
	ds_read_b128 v[104:107], v116 offset:13888
	ds_read_b128 v[112:115], v116 offset:16128
	s_waitcnt lgkmcnt(7)
	ds_read_b128 v[116:119], v116 offset:16192
	v_mfma_f32_16x16x32_bf16 v[156:159], v[120:123], v[0:3], v[124:127]
	v_mfma_f32_16x16x32_bf16 v[164:167], v[132:135], v[0:3], v[124:127]
	v_mfma_f32_16x16x32_bf16 v[172:175], v[144:147], v[0:3], v[124:127]
	v_mfma_f32_16x16x32_bf16 v[180:183], v[152:155], v[0:3], v[124:127]
	v_mfma_f32_16x16x32_bf16 v[156:159], v[128:131], v[4:7], v[156:159]
	v_mfma_f32_16x16x32_bf16 v[164:167], v[136:139], v[4:7], v[164:167]
	v_mfma_f32_16x16x32_bf16 v[172:175], v[148:151], v[4:7], v[172:175]
	v_mfma_f32_16x16x32_bf16 v[180:183], v[140:143], v[4:7], v[180:183]
	v_mfma_f32_16x16x32_bf16 v[184:187], v[120:123], v[8:11], v[124:127]
	v_mfma_f32_16x16x32_bf16 v[176:179], v[132:135], v[8:11], v[124:127]
	v_mfma_f32_16x16x32_bf16 v[168:171], v[144:147], v[8:11], v[124:127]
	v_mfma_f32_16x16x32_bf16 v[160:163], v[152:155], v[8:11], v[124:127]
	s_nop 1
	v_mfma_f32_16x16x32_bf16 v[184:187], v[128:131], v[12:15], v[184:187]
	v_exp_f32_e32 v156, v156
	v_exp_f32_e32 v157, v157
	v_exp_f32_e32 v158, v158
	v_exp_f32_e32 v159, v159
	v_mfma_f32_16x16x32_bf16 v[176:179], v[136:139], v[12:15], v[176:179]
	v_exp_f32_e32 v164, v164
	v_exp_f32_e32 v165, v165
	v_exp_f32_e32 v166, v166
	v_exp_f32_e32 v167, v167
	v_mfma_f32_16x16x32_bf16 v[168:171], v[148:151], v[12:15], v[168:171]
	v_exp_f32_e32 v172, v172
	v_exp_f32_e32 v173, v173
	v_exp_f32_e32 v174, v174
	v_exp_f32_e32 v175, v175
	v_mfma_f32_16x16x32_bf16 v[160:163], v[140:143], v[12:15], v[160:163]
	v_exp_f32_e32 v180, v180
	v_exp_f32_e32 v181, v181
	v_exp_f32_e32 v182, v182
	v_exp_f32_e32 v183, v183
	v_pk_add_f32 v[254:255], v[156:157], v[158:159]
	v_pk_add_f32 v[254:255], v[254:255], v[164:165]
	v_pk_add_f32 v[254:255], v[254:255], v[166:167]
	v_cvt_pk_bf16_f32 v156, v156, v157
	v_cvt_pk_bf16_f32 v157, v158, v159
	v_cvt_pk_bf16_f32 v158, v164, v165
	v_cvt_pk_bf16_f32 v159, v166, v167
	v_pk_add_f32 v[164:165], v[172:173], v[174:175]
	v_pk_add_f32 v[164:165], v[164:165], v[180:181]
	v_pk_add_f32 v[164:165], v[164:165], v[182:183]
	v_cvt_pk_bf16_f32 v172, v172, v173
	v_cvt_pk_bf16_f32 v173, v174, v175
	v_cvt_pk_bf16_f32 v174, v180, v181
	v_cvt_pk_bf16_f32 v175, v182, v183
	v_pk_add_f32 v[254:255], v[254:255], v[164:165]
	v_add_f32_e32 v244, v244, v254
	v_add_f32_e32 v244, v244, v255
	s_waitcnt lgkmcnt(0)
; DI void nsa_item(const Params& p, int bk, int qb, char* smem, float Mb) {
;     ...
;                 for (int g = 0; g < 3; ++g) {
;                     f32x4 st[4];
;                     st_from(kf, qf[g], st, -Ml);
;                     if (diag) {
; #pragma unroll
;                         for (int k4 = 0; k4 < 4; ++k4)
; #pragma unroll
;                             for (int ii = 0; ii < 4; ++ii) {
;                                 const float pv = (j * 64 + k4 * 16 + fq * 4 + ii <= tq) ? __builtin_amdgcn_exp2f(st[k4][ii]) : 0.f;
;                                 st[k4][ii] = pv; ls[g] += pv;
;                             }
;                     } else {
; #pragma unroll
;                         for (int k4 = 0; k4 < 4; ++k4)
; #pragma unroll
;                             for (int ii = 0; ii < 4; ++ii) { const float pv = __builtin_amdgcn_exp2f(st[k4][ii]); st[k4][ii] = pv; ls[g] += pv; }
;                     }
;                     pv_from(vf, st, o[g]);
;                 }
;             }
;             lstore(bsel ^ 1);
;             __syncthreads();
;             bsel ^= 1; j = jn; m = mn;
	s_nop 1
	v_mfma_f32_16x16x32_bf16 v[68:71], v[108:111], v[156:159], v[68:71]
	v_exp_f32_e32 v184, v184
	v_mfma_f32_16x16x32_bf16 v[64:67], v[92:95], v[156:159], v[64:67]
	v_exp_f32_e32 v185, v185
	v_mfma_f32_16x16x32_bf16 v[60:63], v[100:103], v[156:159], v[60:63]
	v_exp_f32_e32 v186, v186
	v_mfma_f32_16x16x32_bf16 v[56:59], v[112:115], v[156:159], v[56:59]
	v_exp_f32_e32 v187, v187
	v_mfma_f32_16x16x32_bf16 v[68:71], v[88:91], v[172:175], v[68:71]
	v_exp_f32_e32 v176, v176
	v_mfma_f32_16x16x32_bf16 v[64:67], v[96:99], v[172:175], v[64:67]
	v_exp_f32_e32 v177, v177
	v_mfma_f32_16x16x32_bf16 v[60:63], v[104:107], v[172:175], v[60:63]
	v_exp_f32_e32 v178, v178
	v_mfma_f32_16x16x32_bf16 v[56:59], v[116:119], v[172:175], v[56:59]
	v_exp_f32_e32 v179, v179
	v_mfma_f32_16x16x32_bf16 v[156:159], v[120:123], v[16:19], v[124:127]
	v_exp_f32_e32 v168, v168
	v_mfma_f32_16x16x32_bf16 v[164:167], v[132:135], v[16:19], v[124:127]
	v_exp_f32_e32 v169, v169
	v_mfma_f32_16x16x32_bf16 v[172:175], v[144:147], v[16:19], v[124:127]
	v_exp_f32_e32 v170, v170
	v_mfma_f32_16x16x32_bf16 v[180:183], v[152:155], v[16:19], v[124:127]
	v_exp_f32_e32 v171, v171
	v_mfma_f32_16x16x32_bf16 v[156:159], v[128:131], v[20:23], v[156:159]
	v_exp_f32_e32 v160, v160
	v_mfma_f32_16x16x32_bf16 v[164:167], v[136:139], v[20:23], v[164:167]
	v_exp_f32_e32 v161, v161
	v_mfma_f32_16x16x32_bf16 v[172:175], v[148:151], v[20:23], v[172:175]
	v_exp_f32_e32 v162, v162
	v_mfma_f32_16x16x32_bf16 v[180:183], v[140:143], v[20:23], v[180:183]
	v_exp_f32_e32 v163, v163
	v_pk_add_f32 v[254:255], v[184:185], v[186:187]
	v_pk_add_f32 v[254:255], v[254:255], v[176:177]
	v_pk_add_f32 v[254:255], v[254:255], v[178:179]
	v_cvt_pk_bf16_f32 v184, v184, v185
	v_cvt_pk_bf16_f32 v185, v186, v187
	v_cvt_pk_bf16_f32 v186, v176, v177
	v_cvt_pk_bf16_f32 v187, v178, v179
	v_pk_add_f32 v[176:177], v[168:169], v[170:171]
	v_pk_add_f32 v[176:177], v[176:177], v[160:161]
	v_pk_add_f32 v[176:177], v[176:177], v[162:163]
	v_cvt_pk_bf16_f32 v168, v168, v169
	v_cvt_pk_bf16_f32 v169, v170, v171
	v_cvt_pk_bf16_f32 v170, v160, v161
	v_cvt_pk_bf16_f32 v171, v162, v163
	v_pk_add_f32 v[254:255], v[254:255], v[176:177]
	v_add_f32_e32 v243, v243, v254
	v_add_f32_e32 v243, v243, v255
	s_nop 1
	v_mfma_f32_16x16x32_bf16 v[52:55], v[108:111], v[184:187], v[52:55]
	v_exp_f32_e32 v156, v156
	v_exp_f32_e32 v157, v157
	v_mfma_f32_16x16x32_bf16 v[48:51], v[92:95], v[184:187], v[48:51]
	v_exp_f32_e32 v158, v158
	v_exp_f32_e32 v159, v159
	v_mfma_f32_16x16x32_bf16 v[44:47], v[100:103], v[184:187], v[44:47]
	v_exp_f32_e32 v164, v164
	v_exp_f32_e32 v165, v165
	v_mfma_f32_16x16x32_bf16 v[40:43], v[112:115], v[184:187], v[40:43]
	v_exp_f32_e32 v166, v166
	v_exp_f32_e32 v167, v167
	v_mfma_f32_16x16x32_bf16 v[52:55], v[88:91], v[168:171], v[52:55]
	v_exp_f32_e32 v172, v172
	v_exp_f32_e32 v173, v173
	v_mfma_f32_16x16x32_bf16 v[48:51], v[96:99], v[168:171], v[48:51]
	v_exp_f32_e32 v174, v174
	v_exp_f32_e32 v175, v175
	v_mfma_f32_16x16x32_bf16 v[44:47], v[104:107], v[168:171], v[44:47]
	v_exp_f32_e32 v180, v180
	v_exp_f32_e32 v181, v181
	v_mfma_f32_16x16x32_bf16 v[40:43], v[116:119], v[168:171], v[40:43]
	v_exp_f32_e32 v182, v182
	v_exp_f32_e32 v183, v183
	v_pk_add_f32 v[254:255], v[156:157], v[158:159]
	v_pk_add_f32 v[254:255], v[254:255], v[164:165]
	v_pk_add_f32 v[254:255], v[254:255], v[166:167]
	v_cvt_pk_bf16_f32 v156, v156, v157
	v_cvt_pk_bf16_f32 v157, v158, v159
	v_cvt_pk_bf16_f32 v158, v164, v165
	v_cvt_pk_bf16_f32 v159, v166, v167
	v_pk_add_f32 v[164:165], v[172:173], v[174:175]
	v_pk_add_f32 v[164:165], v[164:165], v[180:181]
	v_pk_add_f32 v[164:165], v[164:165], v[182:183]
	v_cvt_pk_bf16_f32 v172, v172, v173
	v_cvt_pk_bf16_f32 v173, v174, v175
	v_cvt_pk_bf16_f32 v174, v180, v181
	v_cvt_pk_bf16_f32 v175, v182, v183
	v_pk_add_f32 v[254:255], v[254:255], v[164:165]
	v_add_f32_e32 v241, v241, v254
	v_add_f32_e32 v241, v241, v255
	s_or_b64 exec, exec, s[12:13]
	s_and_b64 s[4:5], exec, s[4:5]
	s_or_b64 s[10:11], s[4:5], s[10:11]
	s_xor_b32 s22, s22, 1
	s_mul_i32 s4, s22, 0x4800
	v_add_u32_e32 v254, s4, v195
	v_readlane_b32 s2, v249, 29
	s_waitcnt vmcnt(3)
	ds_write_b128 v254, v[72:75]
	v_mfma_f32_16x16x32_bf16 v[36:39], v[108:111], v[156:159], v[36:39]
	v_mfma_f32_16x16x32_bf16 v[32:35], v[92:95], v[156:159], v[32:35]
	s_waitcnt vmcnt(2)
	ds_write_b128 v254, v[76:79] offset:4608
	v_lshl_add_u32 v72, v242, 3, s2
	ds_read_b64 v[72:73], v72
	v_mfma_f32_16x16x32_bf16 v[28:31], v[100:103], v[156:159], v[28:31]
	v_mfma_f32_16x16x32_bf16 v[24:27], v[112:115], v[156:159], v[24:27]
	s_waitcnt vmcnt(1)
	ds_write_b128 v254, v[80:83] offset:9216
	v_mfma_f32_16x16x32_bf16 v[36:39], v[88:91], v[172:175], v[36:39]
	v_mfma_f32_16x16x32_bf16 v[32:35], v[96:99], v[172:175], v[32:35]
	s_waitcnt vmcnt(0)
	ds_write_b128 v254, v[84:87] offset:13824
	v_mfma_f32_16x16x32_bf16 v[28:31], v[104:107], v[172:175], v[28:31]
	v_mfma_f32_16x16x32_bf16 v[24:27], v[116:119], v[172:175], v[24:27]
	s_setprio 0
	s_branch .Lsel_bot3
